# sel pair prologue: for full lists wait only for the q rows (vmcnt 13) so the first gathered block and ACC DMA stay in flight during step A
# baseline (speedup 1.0000x reference)
; #define LAS __attribute__((address_space(3)))
; #define SEL_IDX(i) __shfl(myidx, (i) < last ? (i) : last)
; __device__ __forceinline__ void phase_sel(const Params& p, LAS unsigned char* lds, const bf16_t* Z, const float* G, const unsigned char* K8, const unsigned char* V8T, const float* ACC, const int* IDX, bf16_t* Mixed, int tid, int wid, int lane) {
;     ...
;         long qf[2];
;         { const u32x2 qa = bf8_to_fp8(qr0), qb2 = bf8_to_fp8(qr1); qf[0] = mk64(qa.x, qa.y); qf[1] = mk64(qb2.x, qb2.y); }
;         const int nblk = __builtin_popcountll(__ballot(myidx >= 0));
;         const int head = g * 4 + (cc & 3);
;         const float gate_pre = G[row * 32 + 8 + head * 3 + 1];
;         LAS unsigned char* land = lds + 32768 + wid * 4096;
; #pragma unroll
;         for (int d = 0; d < 4; ++d) __builtin_amdgcn_global_load_lds((const unsigned*)(ACC + row * 512 + head * 64 + 16 * d + 4 * q4), (LAS unsigned*)(land + d * 1024), 16, 0, 0);
;         float m = NEG, l = 0.f; f32x4 o[4];
; #pragma unroll
;         for (int d = 0; d < 4; ++d) o[d] = (f32x4){0.f, 0.f, 0.f, 0.f};
;         const unsigned char* Kb = K8 + (size_t)bg * SEQ * 64;
;         const unsigned char* Vb = V8T + (size_t)bg * SEQ * 64;
;         SelBuf b0, b1, b2, b3;
;         const int last = nblk - 1;
;     ...
;         int j0 = SEL_IDX(0), j1 = SEL_IDX(1), j2 = SEL_IDX(2), j3 = SEL_IDX(3);
;         sel_load_any(b0, Kb, Vb, lds, j0, cur, cc, q4); sel_load_any(b1, Kb, Vb, lds, j1, cur, cc, q4); sel_load_any(b2, Kb, Vb, lds, j2, cur, cc, q4); sel_load_any(b3, Kb, Vb, lds, j3, cur, cc, q4);
.LBB0_646:
	s_cmp_lt_u32 s51, 16
	s_cbranch_scc1 .Lsel_strict
	s_cmp_lg_u32 s26, 16
	s_cbranch_scc1 .Lsel_strict
	s_waitcnt vmcnt(13)
	s_branch .Lsel_qcvt

; #define LAS __attribute__((address_space(3)))
; #define SEL_IDX(i) __shfl(myidx, (i) < last ? (i) : last)
; __device__ __forceinline__ void phase_sel(const Params& p, LAS unsigned char* lds, const bf16_t* Z, const float* G, const unsigned char* K8, const unsigned char* V8T, const float* ACC, const int* IDX, bf16_t* Mixed, int tid, int wid, int lane) {
;     ...
;         long qf[2];
;         { const u32x2 qa = bf8_to_fp8(qr0), qb2 = bf8_to_fp8(qr1); qf[0] = mk64(qa.x, qa.y); qf[1] = mk64(qb2.x, qb2.y); }
;         const int nblk = __builtin_popcountll(__ballot(myidx >= 0));
;         const int head = g * 4 + (cc & 3);
;         const float gate_pre = G[row * 32 + 8 + head * 3 + 1];
;         LAS unsigned char* land = lds + 32768 + wid * 4096;
; #pragma unroll
;         for (int d = 0; d < 4; ++d) __builtin_amdgcn_global_load_lds((const unsigned*)(ACC + row * 512 + head * 64 + 16 * d + 4 * q4), (LAS unsigned*)(land + d * 1024), 16, 0, 0);
;         float m = NEG, l = 0.f; f32x4 o[4];
; #pragma unroll
;         for (int d = 0; d < 4; ++d) o[d] = (f32x4){0.f, 0.f, 0.f, 0.f};
;         const unsigned char* Kb = K8 + (size_t)bg * SEQ * 64;
;         const unsigned char* Vb = V8T + (size_t)bg * SEQ * 64;
;         SelBuf b0, b1, b2, b3;
;         const int last = nblk - 1;
;     ...
;         int j0 = SEL_IDX(0), j1 = SEL_IDX(1), j2 = SEL_IDX(2), j3 = SEL_IDX(3);
;         sel_load_any(b0, Kb, Vb, lds, j0, cur, cc, q4); sel_load_any(b1, Kb, Vb, lds, j1, cur, cc, q4); sel_load_any(b2, Kb, Vb, lds, j2, cur, cc, q4); sel_load_any(b3, Kb, Vb, lds, j3, cur, cc, q4);
;         for (int k = 0; k < nblk; k += 4) {
.Lsel_qcvt:
	v_lshlrev_b32_e32 v0, 16, v110
	v_and_b32_e32 v110, 0xffff0000, v110
	v_cvt_pk_fp8_f32 v208, v0, v110
	v_lshlrev_b32_e32 v0, 16, v112
	v_and_b32_e32 v110, 0xffff0000, v112
	v_cvt_pk_fp8_f32 v209, v0, v110
	v_lshlrev_b32_e32 v0, 16, v113
	v_and_b32_e32 v110, 0xffff0000, v113
	v_cvt_pk_fp8_f32 v209, v0, v110 op_sel:[0,0,1]
	v_lshlrev_b32_e32 v0, 16, v98
	v_and_b32_e32 v98, 0xffff0000, v98
	v_cvt_pk_fp8_f32 v210, v0, v98
	v_lshlrev_b32_e32 v0, 16, v100
	v_and_b32_e32 v98, 0xffff0000, v100
	v_cvt_pk_fp8_f32 v211, v0, v98
	v_lshlrev_b32_e32 v140, 16, v111
	v_and_b32_e32 v111, 0xffff0000, v111
	v_lshlrev_b32_e32 v110, 16, v99
	v_and_b32_e32 v99, 0xffff0000, v99
	v_lshlrev_b32_e32 v0, 16, v101
	v_and_b32_e32 v98, 0xffff0000, v101
	v_cvt_pk_fp8_f32 v208, v140, v111 op_sel:[0,0,1]
	v_cvt_pk_fp8_f32 v210, v110, v99 op_sel:[0,0,1]
	v_cvt_pk_fp8_f32 v211, v0, v98 op_sel:[0,0,1]
	v_mov_b32_e32 v249, 0
	v_lshl_add_u64 v[212:213], v[138:139], 0, v[196:197]
	v_mov_b32_e32 v0, 0xf149f2ca
	s_mov_b32 s70, 0
	v_mov_b32_e32 v142, 0
	v_mov_b32_e32 v143, v249
	v_mov_b32_e32 v144, v249
	v_mov_b32_e32 v145, v249
	v_mov_b32_e32 v138, v249
	v_mov_b32_e32 v139, v249
	v_mov_b32_e32 v140, v249
	v_mov_b32_e32 v141, v249
	v_mov_b32_e32 v110, v249
	v_mov_b32_e32 v111, v249
	v_mov_b32_e32 v112, v249
	v_mov_b32_e32 v113, v249
	v_mov_b32_e32 v98, v249
	v_mov_b32_e32 v99, v249
	v_mov_b32_e32 v100, v249
	v_mov_b32_e32 v101, v249
	s_cmp_lt_u32 s51, 16
	s_cbranch_scc1 .LBB0_647
	s_cmp_lg_u32 s26, 16
	s_cbranch_scc1 .LBB0_647
	s_branch .Lsr_647
